# norm1 and norm2 latent-row loops rewritten by hand: per-row rstd computed once per row in lanes, wide LDS partial-sum stores
# speedup vs baseline: 1.0131x; 1.0131x over previous
.LBB0_123:
	v_mbcnt_lo_u32_b32 v112, -1, 0
	v_mbcnt_hi_u32_b32 v112, -1, v112
	v_and_b32_e32 v112, 15, v112
	v_lshlrev_b32_e32 v92, 2, v112
	s_lshl_b32 s17, s3, 6
	v_mov_b32_e32 v91, s17
	s_mov_b32 s12, 0x2000
	s_mov_b32 s13, 0
.Lnm_n1_loop:
	s_ashr_i32 s11, s10, 31
	s_lshl_b64 s[0:1], s[10:11], 13
	v_lshl_add_u64 v[110:111], v[82:83], 0, s[0:1]
	global_load_dwordx4 v[4:7], v[110:111], off
	s_add_u32 s0, s0, 0x2000
	s_addc_u32 s1, s1, 0
	v_lshl_add_u64 v[110:111], v[82:83], 0, s[0:1]
	global_load_dwordx4 v[8:11], v[110:111], off
	s_add_u32 s0, s0, 0x2000
	s_addc_u32 s1, s1, 0
	v_lshl_add_u64 v[110:111], v[82:83], 0, s[0:1]
	global_load_dwordx4 v[12:15], v[110:111], off
	s_add_u32 s0, s0, 0x2000
	s_addc_u32 s1, s1, 0
	v_lshl_add_u64 v[110:111], v[82:83], 0, s[0:1]
	global_load_dwordx4 v[16:19], v[110:111], off
	s_add_u32 s0, s0, 0x2000
	s_addc_u32 s1, s1, 0
	v_lshl_add_u64 v[110:111], v[82:83], 0, s[0:1]
	global_load_dwordx4 v[20:23], v[110:111], off
	s_add_u32 s0, s0, 0x2000
	s_addc_u32 s1, s1, 0
	v_lshl_add_u64 v[110:111], v[82:83], 0, s[0:1]
	global_load_dwordx4 v[24:27], v[110:111], off
	s_add_u32 s0, s0, 0x2000
	s_addc_u32 s1, s1, 0
	v_lshl_add_u64 v[110:111], v[82:83], 0, s[0:1]
	global_load_dwordx4 v[28:31], v[110:111], off
	s_add_u32 s0, s0, 0x2000
	s_addc_u32 s1, s1, 0
	v_lshl_add_u64 v[110:111], v[82:83], 0, s[0:1]
	global_load_dwordx4 v[32:35], v[110:111], off
	s_add_u32 s0, s0, 0x2000
	s_addc_u32 s1, s1, 0
	v_lshl_add_u64 v[110:111], v[82:83], 0, s[0:1]
	global_load_dwordx4 v[36:39], v[110:111], off
	s_add_u32 s0, s0, 0x2000
	s_addc_u32 s1, s1, 0
	v_lshl_add_u64 v[110:111], v[82:83], 0, s[0:1]
	global_load_dwordx4 v[40:43], v[110:111], off
	s_add_u32 s0, s0, 0x2000
	s_addc_u32 s1, s1, 0
	v_lshl_add_u64 v[110:111], v[82:83], 0, s[0:1]
	global_load_dwordx4 v[44:47], v[110:111], off
	s_add_u32 s0, s0, 0x2000
	s_addc_u32 s1, s1, 0
	v_lshl_add_u64 v[110:111], v[82:83], 0, s[0:1]
	global_load_dwordx4 v[48:51], v[110:111], off
	s_add_u32 s0, s0, 0x2000
	s_addc_u32 s1, s1, 0
	v_lshl_add_u64 v[110:111], v[82:83], 0, s[0:1]
	global_load_dwordx4 v[52:55], v[110:111], off
	s_add_u32 s0, s0, 0x2000
	s_addc_u32 s1, s1, 0
	v_lshl_add_u64 v[110:111], v[82:83], 0, s[0:1]
	global_load_dwordx4 v[56:59], v[110:111], off
	s_add_u32 s0, s0, 0x2000
	s_addc_u32 s1, s1, 0
	v_lshl_add_u64 v[110:111], v[82:83], 0, s[0:1]
	global_load_dwordx4 v[60:63], v[110:111], off
	s_add_u32 s0, s0, 0x2000
	s_addc_u32 s1, s1, 0
	v_lshl_add_u64 v[110:111], v[82:83], 0, s[0:1]
	global_load_dwordx4 v[64:67], v[110:111], off
	s_ashr_i32 s0, s22, 8
	v_mad_i64_i32 v[110:111], s[0:1], s0, v178, v[80:81]
	v_lshl_add_u64 v[112:113], v[110:111], 0, s[12:13]
	global_load_dwordx4 v[118:121], v[112:113], off
	s_mov_b32 s0, 0x0
	s_mov_b32 s1, 0
	v_lshl_add_u64 v[112:113], v[110:111], 0, s[0:1]
	global_load_dwordx4 v[250:253], v[112:113], off
	s_waitcnt vmcnt(17)
	v_mul_f32_e32 v68, v5, v5
	v_mul_f32_e32 v102, v7, v7
	v_fmac_f32_e32 v68, v4, v4
	v_fmac_f32_e32 v102, v6, v6
	v_add_f32_e32 v68, v68, v102
	s_waitcnt vmcnt(16)
	v_mul_f32_e32 v69, v9, v9
	v_mul_f32_e32 v103, v11, v11
	v_fmac_f32_e32 v69, v8, v8
	v_fmac_f32_e32 v103, v10, v10
	v_add_f32_e32 v69, v69, v103
	s_waitcnt vmcnt(15)
	v_mul_f32_e32 v70, v13, v13
	v_mul_f32_e32 v104, v15, v15
	v_fmac_f32_e32 v70, v12, v12
	v_fmac_f32_e32 v104, v14, v14
	v_add_f32_e32 v70, v70, v104
	s_waitcnt vmcnt(14)
	v_mul_f32_e32 v71, v17, v17
	v_mul_f32_e32 v105, v19, v19
	v_fmac_f32_e32 v71, v16, v16
	v_fmac_f32_e32 v105, v18, v18
	v_add_f32_e32 v71, v71, v105
	s_waitcnt vmcnt(13)
	v_mul_f32_e32 v72, v21, v21
	v_mul_f32_e32 v106, v23, v23
	v_fmac_f32_e32 v72, v20, v20
	v_fmac_f32_e32 v106, v22, v22
	v_add_f32_e32 v72, v72, v106
	s_waitcnt vmcnt(12)
	v_mul_f32_e32 v73, v25, v25
	v_mul_f32_e32 v107, v27, v27
	v_fmac_f32_e32 v73, v24, v24
	v_fmac_f32_e32 v107, v26, v26
	v_add_f32_e32 v73, v73, v107
	s_waitcnt vmcnt(11)
	v_mul_f32_e32 v74, v29, v29
	v_mul_f32_e32 v108, v31, v31
	v_fmac_f32_e32 v74, v28, v28
	v_fmac_f32_e32 v108, v30, v30
	v_add_f32_e32 v74, v74, v108
	s_waitcnt vmcnt(10)
	v_mul_f32_e32 v75, v33, v33
	v_mul_f32_e32 v109, v35, v35
	v_fmac_f32_e32 v75, v32, v32
	v_fmac_f32_e32 v109, v34, v34
	v_add_f32_e32 v75, v75, v109
	s_waitcnt vmcnt(9)
	v_mul_f32_e32 v94, v37, v37
	v_mul_f32_e32 v110, v39, v39
	v_fmac_f32_e32 v94, v36, v36
	v_fmac_f32_e32 v110, v38, v38
	v_add_f32_e32 v94, v94, v110
	s_waitcnt vmcnt(8)
	v_mul_f32_e32 v95, v41, v41
	v_mul_f32_e32 v111, v43, v43
	v_fmac_f32_e32 v95, v40, v40
	v_fmac_f32_e32 v111, v42, v42
	v_add_f32_e32 v95, v95, v111
	s_waitcnt vmcnt(7)
	v_mul_f32_e32 v96, v45, v45
	v_mul_f32_e32 v112, v47, v47
	v_fmac_f32_e32 v96, v44, v44
	v_fmac_f32_e32 v112, v46, v46
	v_add_f32_e32 v96, v96, v112
	s_waitcnt vmcnt(6)
	v_mul_f32_e32 v97, v49, v49
	v_mul_f32_e32 v113, v51, v51
	v_fmac_f32_e32 v97, v48, v48
	v_fmac_f32_e32 v113, v50, v50
	v_add_f32_e32 v97, v97, v113
	s_waitcnt vmcnt(5)
	v_mul_f32_e32 v98, v53, v53
	v_mul_f32_e32 v114, v55, v55
	v_fmac_f32_e32 v98, v52, v52
	v_fmac_f32_e32 v114, v54, v54
	v_add_f32_e32 v98, v98, v114
	s_waitcnt vmcnt(4)
	v_mul_f32_e32 v99, v57, v57
	v_mul_f32_e32 v115, v59, v59
	v_fmac_f32_e32 v99, v56, v56
	v_fmac_f32_e32 v115, v58, v58
	v_add_f32_e32 v99, v99, v115
	s_waitcnt vmcnt(3)
	v_mul_f32_e32 v100, v61, v61
	v_mul_f32_e32 v116, v63, v63
	v_fmac_f32_e32 v100, v60, v60
	v_fmac_f32_e32 v116, v62, v62
	v_add_f32_e32 v100, v100, v116
	s_waitcnt vmcnt(2)
	v_mul_f32_e32 v101, v65, v65
	v_mul_f32_e32 v117, v67, v67
	v_fmac_f32_e32 v101, v64, v64
	v_fmac_f32_e32 v117, v66, v66
	v_add_f32_e32 v101, v101, v117
	ds_bpermute_b32 v102, v85, v68
	ds_bpermute_b32 v103, v85, v69
	ds_bpermute_b32 v104, v85, v70
	ds_bpermute_b32 v105, v85, v71
	ds_bpermute_b32 v106, v85, v72
	ds_bpermute_b32 v107, v85, v73
	ds_bpermute_b32 v108, v85, v74
	ds_bpermute_b32 v109, v85, v75
	ds_bpermute_b32 v110, v85, v94
	ds_bpermute_b32 v111, v85, v95
	ds_bpermute_b32 v112, v85, v96
	ds_bpermute_b32 v113, v85, v97
	ds_bpermute_b32 v114, v85, v98
	ds_bpermute_b32 v115, v85, v99
	ds_bpermute_b32 v116, v85, v100
	ds_bpermute_b32 v117, v85, v101
	s_waitcnt lgkmcnt(15)
	v_add_f32_e32 v68, v68, v102
	s_waitcnt lgkmcnt(14)
	v_add_f32_e32 v69, v69, v103
	s_waitcnt lgkmcnt(13)
	v_add_f32_e32 v70, v70, v104
	s_waitcnt lgkmcnt(12)
	v_add_f32_e32 v71, v71, v105
	s_waitcnt lgkmcnt(11)
	v_add_f32_e32 v72, v72, v106
	s_waitcnt lgkmcnt(10)
	v_add_f32_e32 v73, v73, v107
	s_waitcnt lgkmcnt(9)
	v_add_f32_e32 v74, v74, v108
	s_waitcnt lgkmcnt(8)
	v_add_f32_e32 v75, v75, v109
	s_waitcnt lgkmcnt(7)
	v_add_f32_e32 v94, v94, v110
	s_waitcnt lgkmcnt(6)
	v_add_f32_e32 v95, v95, v111
	s_waitcnt lgkmcnt(5)
	v_add_f32_e32 v96, v96, v112
	s_waitcnt lgkmcnt(4)
	v_add_f32_e32 v97, v97, v113
	s_waitcnt lgkmcnt(3)
	v_add_f32_e32 v98, v98, v114
	s_waitcnt lgkmcnt(2)
	v_add_f32_e32 v99, v99, v115
	s_waitcnt lgkmcnt(1)
	v_add_f32_e32 v100, v100, v116
	s_waitcnt lgkmcnt(0)
	v_add_f32_e32 v101, v101, v117
	ds_bpermute_b32 v102, v86, v68
	ds_bpermute_b32 v103, v86, v69
	ds_bpermute_b32 v104, v86, v70
	ds_bpermute_b32 v105, v86, v71
	ds_bpermute_b32 v106, v86, v72
	ds_bpermute_b32 v107, v86, v73
	ds_bpermute_b32 v108, v86, v74
	ds_bpermute_b32 v109, v86, v75
	ds_bpermute_b32 v110, v86, v94
	ds_bpermute_b32 v111, v86, v95
	ds_bpermute_b32 v112, v86, v96
	ds_bpermute_b32 v113, v86, v97
	ds_bpermute_b32 v114, v86, v98
	ds_bpermute_b32 v115, v86, v99
	ds_bpermute_b32 v116, v86, v100
	ds_bpermute_b32 v117, v86, v101
	s_waitcnt lgkmcnt(15)
	v_add_f32_e32 v68, v68, v102
	s_waitcnt lgkmcnt(14)
	v_add_f32_e32 v69, v69, v103
	s_waitcnt lgkmcnt(13)
	v_add_f32_e32 v70, v70, v104
	s_waitcnt lgkmcnt(12)
	v_add_f32_e32 v71, v71, v105
	s_waitcnt lgkmcnt(11)
	v_add_f32_e32 v72, v72, v106
	s_waitcnt lgkmcnt(10)
	v_add_f32_e32 v73, v73, v107
	s_waitcnt lgkmcnt(9)
	v_add_f32_e32 v74, v74, v108
	s_waitcnt lgkmcnt(8)
	v_add_f32_e32 v75, v75, v109
	s_waitcnt lgkmcnt(7)
	v_add_f32_e32 v94, v94, v110
	s_waitcnt lgkmcnt(6)
	v_add_f32_e32 v95, v95, v111
	s_waitcnt lgkmcnt(5)
	v_add_f32_e32 v96, v96, v112
	s_waitcnt lgkmcnt(4)
	v_add_f32_e32 v97, v97, v113
	s_waitcnt lgkmcnt(3)
	v_add_f32_e32 v98, v98, v114
	s_waitcnt lgkmcnt(2)
	v_add_f32_e32 v99, v99, v115
	s_waitcnt lgkmcnt(1)
	v_add_f32_e32 v100, v100, v116
	s_waitcnt lgkmcnt(0)
	v_add_f32_e32 v101, v101, v117
	ds_bpermute_b32 v102, v87, v68
	ds_bpermute_b32 v103, v87, v69
	ds_bpermute_b32 v104, v87, v70
	ds_bpermute_b32 v105, v87, v71
	ds_bpermute_b32 v106, v87, v72
	ds_bpermute_b32 v107, v87, v73
	ds_bpermute_b32 v108, v87, v74
	ds_bpermute_b32 v109, v87, v75
	ds_bpermute_b32 v110, v87, v94
	ds_bpermute_b32 v111, v87, v95
	ds_bpermute_b32 v112, v87, v96
	ds_bpermute_b32 v113, v87, v97
	ds_bpermute_b32 v114, v87, v98
	ds_bpermute_b32 v115, v87, v99
	ds_bpermute_b32 v116, v87, v100
	ds_bpermute_b32 v117, v87, v101
	s_waitcnt lgkmcnt(15)
	v_add_f32_e32 v68, v68, v102
	s_waitcnt lgkmcnt(14)
	v_add_f32_e32 v69, v69, v103
	s_waitcnt lgkmcnt(13)
	v_add_f32_e32 v70, v70, v104
	s_waitcnt lgkmcnt(12)
	v_add_f32_e32 v71, v71, v105
	s_waitcnt lgkmcnt(11)
	v_add_f32_e32 v72, v72, v106
	s_waitcnt lgkmcnt(10)
	v_add_f32_e32 v73, v73, v107
	s_waitcnt lgkmcnt(9)
	v_add_f32_e32 v74, v74, v108
	s_waitcnt lgkmcnt(8)
	v_add_f32_e32 v75, v75, v109
	s_waitcnt lgkmcnt(7)
	v_add_f32_e32 v94, v94, v110
	s_waitcnt lgkmcnt(6)
	v_add_f32_e32 v95, v95, v111
	s_waitcnt lgkmcnt(5)
	v_add_f32_e32 v96, v96, v112
	s_waitcnt lgkmcnt(4)
	v_add_f32_e32 v97, v97, v113
	s_waitcnt lgkmcnt(3)
	v_add_f32_e32 v98, v98, v114
	s_waitcnt lgkmcnt(2)
	v_add_f32_e32 v99, v99, v115
	s_waitcnt lgkmcnt(1)
	v_add_f32_e32 v100, v100, v116
	s_waitcnt lgkmcnt(0)
	v_add_f32_e32 v101, v101, v117
	ds_bpermute_b32 v102, v88, v68
	ds_bpermute_b32 v103, v88, v69
	ds_bpermute_b32 v104, v88, v70
	ds_bpermute_b32 v105, v88, v71
	ds_bpermute_b32 v106, v88, v72
	ds_bpermute_b32 v107, v88, v73
	ds_bpermute_b32 v108, v88, v74
	ds_bpermute_b32 v109, v88, v75
	ds_bpermute_b32 v110, v88, v94
	ds_bpermute_b32 v111, v88, v95
	ds_bpermute_b32 v112, v88, v96
	ds_bpermute_b32 v113, v88, v97
	ds_bpermute_b32 v114, v88, v98
	ds_bpermute_b32 v115, v88, v99
	ds_bpermute_b32 v116, v88, v100
	ds_bpermute_b32 v117, v88, v101
	s_waitcnt lgkmcnt(15)
	v_add_f32_e32 v68, v68, v102
	s_waitcnt lgkmcnt(14)
	v_add_f32_e32 v69, v69, v103
	s_waitcnt lgkmcnt(13)
	v_add_f32_e32 v70, v70, v104
	s_waitcnt lgkmcnt(12)
	v_add_f32_e32 v71, v71, v105
	s_waitcnt lgkmcnt(11)
	v_add_f32_e32 v72, v72, v106
	s_waitcnt lgkmcnt(10)
	v_add_f32_e32 v73, v73, v107
	s_waitcnt lgkmcnt(9)
	v_add_f32_e32 v74, v74, v108
	s_waitcnt lgkmcnt(8)
	v_add_f32_e32 v75, v75, v109
	s_waitcnt lgkmcnt(7)
	v_add_f32_e32 v94, v94, v110
	s_waitcnt lgkmcnt(6)
	v_add_f32_e32 v95, v95, v111
	s_waitcnt lgkmcnt(5)
	v_add_f32_e32 v96, v96, v112
	s_waitcnt lgkmcnt(4)
	v_add_f32_e32 v97, v97, v113
	s_waitcnt lgkmcnt(3)
	v_add_f32_e32 v98, v98, v114
	s_waitcnt lgkmcnt(2)
	v_add_f32_e32 v99, v99, v115
	s_waitcnt lgkmcnt(1)
	v_add_f32_e32 v100, v100, v116
	s_waitcnt lgkmcnt(0)
	v_add_f32_e32 v101, v101, v117
	ds_bpermute_b32 v102, v89, v68
	ds_bpermute_b32 v103, v89, v69
	ds_bpermute_b32 v104, v89, v70
	ds_bpermute_b32 v105, v89, v71
	ds_bpermute_b32 v106, v89, v72
	ds_bpermute_b32 v107, v89, v73
	ds_bpermute_b32 v108, v89, v74
	ds_bpermute_b32 v109, v89, v75
	ds_bpermute_b32 v110, v89, v94
	ds_bpermute_b32 v111, v89, v95
	ds_bpermute_b32 v112, v89, v96
	ds_bpermute_b32 v113, v89, v97
	ds_bpermute_b32 v114, v89, v98
	ds_bpermute_b32 v115, v89, v99
	ds_bpermute_b32 v116, v89, v100
	ds_bpermute_b32 v117, v89, v101
	s_waitcnt lgkmcnt(15)
	v_add_f32_e32 v68, v68, v102
	s_waitcnt lgkmcnt(14)
	v_add_f32_e32 v69, v69, v103
	s_waitcnt lgkmcnt(13)
	v_add_f32_e32 v70, v70, v104
	s_waitcnt lgkmcnt(12)
	v_add_f32_e32 v71, v71, v105
	s_waitcnt lgkmcnt(11)
	v_add_f32_e32 v72, v72, v106
	s_waitcnt lgkmcnt(10)
	v_add_f32_e32 v73, v73, v107
	s_waitcnt lgkmcnt(9)
	v_add_f32_e32 v74, v74, v108
	s_waitcnt lgkmcnt(8)
	v_add_f32_e32 v75, v75, v109
	s_waitcnt lgkmcnt(7)
	v_add_f32_e32 v94, v94, v110
	s_waitcnt lgkmcnt(6)
	v_add_f32_e32 v95, v95, v111
	s_waitcnt lgkmcnt(5)
	v_add_f32_e32 v96, v96, v112
	s_waitcnt lgkmcnt(4)
	v_add_f32_e32 v97, v97, v113
	s_waitcnt lgkmcnt(3)
	v_add_f32_e32 v98, v98, v114
	s_waitcnt lgkmcnt(2)
	v_add_f32_e32 v99, v99, v115
	s_waitcnt lgkmcnt(1)
	v_add_f32_e32 v100, v100, v116
	s_waitcnt lgkmcnt(0)
	v_add_f32_e32 v101, v101, v117
	ds_bpermute_b32 v102, v90, v68
	ds_bpermute_b32 v103, v90, v69
	ds_bpermute_b32 v104, v90, v70
	ds_bpermute_b32 v105, v90, v71
	ds_bpermute_b32 v106, v90, v72
	ds_bpermute_b32 v107, v90, v73
	ds_bpermute_b32 v108, v90, v74
	ds_bpermute_b32 v109, v90, v75
	ds_bpermute_b32 v110, v90, v94
	ds_bpermute_b32 v111, v90, v95
	ds_bpermute_b32 v112, v90, v96
	ds_bpermute_b32 v113, v90, v97
	ds_bpermute_b32 v114, v90, v98
	ds_bpermute_b32 v115, v90, v99
	ds_bpermute_b32 v116, v90, v100
	ds_bpermute_b32 v117, v90, v101
	s_waitcnt lgkmcnt(15)
	v_add_f32_e32 v68, v68, v102
	s_waitcnt lgkmcnt(14)
	v_add_f32_e32 v69, v69, v103
	s_waitcnt lgkmcnt(13)
	v_add_f32_e32 v70, v70, v104
	s_waitcnt lgkmcnt(12)
	v_add_f32_e32 v71, v71, v105
	s_waitcnt lgkmcnt(11)
	v_add_f32_e32 v72, v72, v106
	s_waitcnt lgkmcnt(10)
	v_add_f32_e32 v73, v73, v107
	s_waitcnt lgkmcnt(9)
	v_add_f32_e32 v74, v74, v108
	s_waitcnt lgkmcnt(8)
	v_add_f32_e32 v75, v75, v109
	s_waitcnt lgkmcnt(7)
	v_add_f32_e32 v94, v94, v110
	s_waitcnt lgkmcnt(6)
	v_add_f32_e32 v95, v95, v111
	s_waitcnt lgkmcnt(5)
	v_add_f32_e32 v96, v96, v112
	s_waitcnt lgkmcnt(4)
	v_add_f32_e32 v97, v97, v113
	s_waitcnt lgkmcnt(3)
	v_add_f32_e32 v98, v98, v114
	s_waitcnt lgkmcnt(2)
	v_add_f32_e32 v99, v99, v115
	s_waitcnt lgkmcnt(1)
	v_add_f32_e32 v100, v100, v116
	s_waitcnt lgkmcnt(0)
	v_add_f32_e32 v101, v101, v117
	s_mov_b64 exec, 1
	ds_write_b128 v91, v[68:71]
	ds_write_b128 v91, v[72:75] offset:16
	ds_write_b128 v91, v[94:97] offset:32
	ds_write_b128 v91, v[98:101] offset:48
	s_mov_b64 exec, -1
	s_waitcnt lgkmcnt(0)
	s_barrier
	ds_read_b32 v102, v92
	ds_read_b32 v103, v92 offset:64
	ds_read_b32 v104, v92 offset:128
	ds_read_b32 v105, v92 offset:192
	ds_read_b32 v106, v92 offset:256
	ds_read_b32 v107, v92 offset:320
	ds_read_b32 v108, v92 offset:384
	ds_read_b32 v109, v92 offset:448
	s_waitcnt lgkmcnt(0)
	v_add_f32_e32 v102, v102, v103
	v_add_f32_e32 v104, v104, v105
	v_add_f32_e32 v106, v106, v107
	v_add_f32_e32 v108, v108, v109
	v_add_f32_e32 v102, v102, v104
	v_add_f32_e32 v106, v106, v108
	v_add_f32_e32 v102, v102, v106
	v_fmamk_f32 v102, v102, 0x3a000000, v173
	v_cmp_gt_f32_e32 vcc, s33, v102
	v_mul_f32_e32 v116, 0x4f800000, v102
	s_nop 1
	v_cndmask_b32_e32 v102, v102, v116, vcc
	v_sqrt_f32_e32 v116, v102
	s_nop 1
	v_add_u32_e32 v111, -1, v116
	v_fma_f32 v112, -v111, v116, v102
	v_cmp_ge_f32_e64 s[14:15], 0, v112
	v_add_u32_e32 v112, 1, v116
	s_nop 1
	v_cndmask_b32_e64 v111, v116, v111, s[14:15]
	v_fma_f32 v116, -v112, v116, v102
	v_cmp_lt_f32_e64 s[14:15], 0, v116
	s_nop 1
	v_cndmask_b32_e64 v116, v111, v112, s[14:15]
	v_mul_f32_e32 v111, 0x37800000, v116
	v_cndmask_b32_e32 v116, v116, v111, vcc
	v_cmp_class_f32_e32 vcc, v102, v174
	s_nop 1
	v_cndmask_b32_e32 v102, v116, v102, vcc
	v_div_scale_f32 v116, s[16:17], v102, v102, 1.0
	v_rcp_f32_e32 v111, v116
	s_nop 0
	v_fma_f32 v112, -v116, v111, 1.0
	v_fmac_f32_e32 v111, v112, v111
	v_div_scale_f32 v112, vcc, 1.0, v102, 1.0
	v_mul_f32_e32 v113, v112, v111
	v_fma_f32 v114, -v116, v113, v112
	v_fmac_f32_e32 v113, v114, v111
	v_fma_f32 v116, -v116, v113, v112
	v_div_fmas_f32 v116, v116, v111, v113
	v_div_fixup_f32 v116, v116, v102, 1.0
	s_waitcnt vmcnt(0)
	v_pk_add_f32 v[118:119], v[118:119], 1.0 op_sel_hi:[1,0]
	v_pk_add_f32 v[120:121], v[120:121], 1.0 op_sel_hi:[1,0]
	v_pk_mul_f32 v[104:105], v[0:1], v[118:119]
	v_pk_mul_f32 v[106:107], v[2:3], v[120:121]
	s_ashr_i32 s11, s10, 31
	s_lshl_b64 s[4:5], s[10:11], 12
	v_readlane_b32 s0, v116, 0
	v_readlane_b32 s1, v116, 1
	v_readlane_b32 s11, v116, 2
	v_readlane_b32 s12, v116, 3
	v_readlane_b32 s13, v116, 4
	v_readlane_b32 s14, v116, 5
	v_readlane_b32 s18, v116, 6
	v_readlane_b32 s19, v116, 7
	s_nop 1
	v_mul_f32_e32 v4, s0, v4
	v_mul_f32_e32 v5, s0, v5
	v_mul_f32_e32 v6, s0, v6
	v_mul_f32_e32 v7, s0, v7
	v_pk_fma_f32 v[4:5], v[104:105], v[4:5], v[250:251]
	v_pk_fma_f32 v[6:7], v[106:107], v[6:7], v[252:253]
	v_cvt_pk_bf16_f32 v4, v4, v5
	v_cvt_pk_bf16_f32 v5, v6, v7
	v_lshl_add_u64 v[108:109], v[76:77], 0, s[4:5]
	global_store_dwordx2 v[108:109], v[4:5], off
	s_add_u32 s4, s4, 0x1000
	s_addc_u32 s5, s5, 0
	v_mul_f32_e32 v8, s1, v8
	v_mul_f32_e32 v9, s1, v9
	v_mul_f32_e32 v10, s1, v10
	v_mul_f32_e32 v11, s1, v11
	v_pk_fma_f32 v[8:9], v[104:105], v[8:9], v[250:251]
	v_pk_fma_f32 v[10:11], v[106:107], v[10:11], v[252:253]
	v_cvt_pk_bf16_f32 v8, v8, v9
	v_cvt_pk_bf16_f32 v9, v10, v11
	v_lshl_add_u64 v[108:109], v[76:77], 0, s[4:5]
	global_store_dwordx2 v[108:109], v[8:9], off
	s_add_u32 s4, s4, 0x1000
	s_addc_u32 s5, s5, 0
	v_mul_f32_e32 v12, s11, v12
	v_mul_f32_e32 v13, s11, v13
	v_mul_f32_e32 v14, s11, v14
	v_mul_f32_e32 v15, s11, v15
	v_pk_fma_f32 v[12:13], v[104:105], v[12:13], v[250:251]
	v_pk_fma_f32 v[14:15], v[106:107], v[14:15], v[252:253]
	v_cvt_pk_bf16_f32 v12, v12, v13
	v_cvt_pk_bf16_f32 v13, v14, v15
	v_lshl_add_u64 v[108:109], v[76:77], 0, s[4:5]
	global_store_dwordx2 v[108:109], v[12:13], off
	s_add_u32 s4, s4, 0x1000
	s_addc_u32 s5, s5, 0
	v_mul_f32_e32 v16, s12, v16
	v_mul_f32_e32 v17, s12, v17
	v_mul_f32_e32 v18, s12, v18
	v_mul_f32_e32 v19, s12, v19
	v_pk_fma_f32 v[16:17], v[104:105], v[16:17], v[250:251]
	v_pk_fma_f32 v[18:19], v[106:107], v[18:19], v[252:253]
	v_cvt_pk_bf16_f32 v16, v16, v17
	v_cvt_pk_bf16_f32 v17, v18, v19
	v_lshl_add_u64 v[108:109], v[76:77], 0, s[4:5]
	global_store_dwordx2 v[108:109], v[16:17], off
	s_add_u32 s4, s4, 0x1000
	s_addc_u32 s5, s5, 0
	v_mul_f32_e32 v20, s13, v20
	v_mul_f32_e32 v21, s13, v21
	v_mul_f32_e32 v22, s13, v22
	v_mul_f32_e32 v23, s13, v23
	v_pk_fma_f32 v[20:21], v[104:105], v[20:21], v[250:251]
	v_pk_fma_f32 v[22:23], v[106:107], v[22:23], v[252:253]
	v_cvt_pk_bf16_f32 v20, v20, v21
	v_cvt_pk_bf16_f32 v21, v22, v23
	v_lshl_add_u64 v[108:109], v[76:77], 0, s[4:5]
	global_store_dwordx2 v[108:109], v[20:21], off
	s_add_u32 s4, s4, 0x1000
	s_addc_u32 s5, s5, 0
	v_mul_f32_e32 v24, s14, v24
	v_mul_f32_e32 v25, s14, v25
	v_mul_f32_e32 v26, s14, v26
	v_mul_f32_e32 v27, s14, v27
	v_pk_fma_f32 v[24:25], v[104:105], v[24:25], v[250:251]
	v_pk_fma_f32 v[26:27], v[106:107], v[26:27], v[252:253]
	v_cvt_pk_bf16_f32 v24, v24, v25
	v_cvt_pk_bf16_f32 v25, v26, v27
	v_lshl_add_u64 v[108:109], v[76:77], 0, s[4:5]
	global_store_dwordx2 v[108:109], v[24:25], off
	s_add_u32 s4, s4, 0x1000
	s_addc_u32 s5, s5, 0
	v_mul_f32_e32 v28, s18, v28
	v_mul_f32_e32 v29, s18, v29
	v_mul_f32_e32 v30, s18, v30
	v_mul_f32_e32 v31, s18, v31
	v_pk_fma_f32 v[28:29], v[104:105], v[28:29], v[250:251]
	v_pk_fma_f32 v[30:31], v[106:107], v[30:31], v[252:253]
	v_cvt_pk_bf16_f32 v28, v28, v29
	v_cvt_pk_bf16_f32 v29, v30, v31
	v_lshl_add_u64 v[108:109], v[76:77], 0, s[4:5]
	global_store_dwordx2 v[108:109], v[28:29], off
	s_add_u32 s4, s4, 0x1000
	s_addc_u32 s5, s5, 0
	v_mul_f32_e32 v32, s19, v32
	v_mul_f32_e32 v33, s19, v33
	v_mul_f32_e32 v34, s19, v34
	v_mul_f32_e32 v35, s19, v35
	v_pk_fma_f32 v[32:33], v[104:105], v[32:33], v[250:251]
	v_pk_fma_f32 v[34:35], v[106:107], v[34:35], v[252:253]
	v_cvt_pk_bf16_f32 v32, v32, v33
	v_cvt_pk_bf16_f32 v33, v34, v35
	v_lshl_add_u64 v[108:109], v[76:77], 0, s[4:5]
	global_store_dwordx2 v[108:109], v[32:33], off
	s_add_u32 s4, s4, 0x1000
	s_addc_u32 s5, s5, 0
	v_readlane_b32 s0, v116, 8
	v_readlane_b32 s1, v116, 9
	v_readlane_b32 s11, v116, 10
	v_readlane_b32 s12, v116, 11
	v_readlane_b32 s13, v116, 12
	v_readlane_b32 s14, v116, 13
	v_readlane_b32 s18, v116, 14
	v_readlane_b32 s19, v116, 15
	s_nop 1
	v_mul_f32_e32 v36, s0, v36
	v_mul_f32_e32 v37, s0, v37
	v_mul_f32_e32 v38, s0, v38
	v_mul_f32_e32 v39, s0, v39
	v_pk_fma_f32 v[36:37], v[104:105], v[36:37], v[250:251]
	v_pk_fma_f32 v[38:39], v[106:107], v[38:39], v[252:253]
	v_cvt_pk_bf16_f32 v36, v36, v37
	v_cvt_pk_bf16_f32 v37, v38, v39
	v_lshl_add_u64 v[108:109], v[76:77], 0, s[4:5]
	global_store_dwordx2 v[108:109], v[36:37], off
	s_add_u32 s4, s4, 0x1000
	s_addc_u32 s5, s5, 0
	v_mul_f32_e32 v40, s1, v40
	v_mul_f32_e32 v41, s1, v41
	v_mul_f32_e32 v42, s1, v42
	v_mul_f32_e32 v43, s1, v43
	v_pk_fma_f32 v[40:41], v[104:105], v[40:41], v[250:251]
	v_pk_fma_f32 v[42:43], v[106:107], v[42:43], v[252:253]
	v_cvt_pk_bf16_f32 v40, v40, v41
	v_cvt_pk_bf16_f32 v41, v42, v43
	v_lshl_add_u64 v[108:109], v[76:77], 0, s[4:5]
	global_store_dwordx2 v[108:109], v[40:41], off
	s_add_u32 s4, s4, 0x1000
	s_addc_u32 s5, s5, 0
	v_mul_f32_e32 v44, s11, v44
	v_mul_f32_e32 v45, s11, v45
	v_mul_f32_e32 v46, s11, v46
	v_mul_f32_e32 v47, s11, v47
	v_pk_fma_f32 v[44:45], v[104:105], v[44:45], v[250:251]
	v_pk_fma_f32 v[46:47], v[106:107], v[46:47], v[252:253]
	v_cvt_pk_bf16_f32 v44, v44, v45
	v_cvt_pk_bf16_f32 v45, v46, v47
	v_lshl_add_u64 v[108:109], v[76:77], 0, s[4:5]
	global_store_dwordx2 v[108:109], v[44:45], off
	s_add_u32 s4, s4, 0x1000
	s_addc_u32 s5, s5, 0
	v_mul_f32_e32 v48, s12, v48
	v_mul_f32_e32 v49, s12, v49
	v_mul_f32_e32 v50, s12, v50
	v_mul_f32_e32 v51, s12, v51
	v_pk_fma_f32 v[48:49], v[104:105], v[48:49], v[250:251]
	v_pk_fma_f32 v[50:51], v[106:107], v[50:51], v[252:253]
	v_cvt_pk_bf16_f32 v48, v48, v49
	v_cvt_pk_bf16_f32 v49, v50, v51
	v_lshl_add_u64 v[108:109], v[76:77], 0, s[4:5]
	global_store_dwordx2 v[108:109], v[48:49], off
	s_add_u32 s4, s4, 0x1000
	s_addc_u32 s5, s5, 0
	v_mul_f32_e32 v52, s13, v52
	v_mul_f32_e32 v53, s13, v53
	v_mul_f32_e32 v54, s13, v54
	v_mul_f32_e32 v55, s13, v55
	v_pk_fma_f32 v[52:53], v[104:105], v[52:53], v[250:251]
	v_pk_fma_f32 v[54:55], v[106:107], v[54:55], v[252:253]
	v_cvt_pk_bf16_f32 v52, v52, v53
	v_cvt_pk_bf16_f32 v53, v54, v55
	v_lshl_add_u64 v[108:109], v[76:77], 0, s[4:5]
	global_store_dwordx2 v[108:109], v[52:53], off
	s_add_u32 s4, s4, 0x1000
	s_addc_u32 s5, s5, 0
	v_mul_f32_e32 v56, s14, v56
	v_mul_f32_e32 v57, s14, v57
	v_mul_f32_e32 v58, s14, v58
	v_mul_f32_e32 v59, s14, v59
	v_pk_fma_f32 v[56:57], v[104:105], v[56:57], v[250:251]
	v_pk_fma_f32 v[58:59], v[106:107], v[58:59], v[252:253]
	v_cvt_pk_bf16_f32 v56, v56, v57
	v_cvt_pk_bf16_f32 v57, v58, v59
	v_lshl_add_u64 v[108:109], v[76:77], 0, s[4:5]
	global_store_dwordx2 v[108:109], v[56:57], off
	s_add_u32 s4, s4, 0x1000
	s_addc_u32 s5, s5, 0
	v_mul_f32_e32 v60, s18, v60
	v_mul_f32_e32 v61, s18, v61
	v_mul_f32_e32 v62, s18, v62
	v_mul_f32_e32 v63, s18, v63
	v_pk_fma_f32 v[60:61], v[104:105], v[60:61], v[250:251]
	v_pk_fma_f32 v[62:63], v[106:107], v[62:63], v[252:253]
	v_cvt_pk_bf16_f32 v60, v60, v61
	v_cvt_pk_bf16_f32 v61, v62, v63
	v_lshl_add_u64 v[108:109], v[76:77], 0, s[4:5]
	global_store_dwordx2 v[108:109], v[60:61], off
	s_add_u32 s4, s4, 0x1000
	s_addc_u32 s5, s5, 0
	v_mul_f32_e32 v64, s19, v64
	v_mul_f32_e32 v65, s19, v65
	v_mul_f32_e32 v66, s19, v66
	v_mul_f32_e32 v67, s19, v67
	v_pk_fma_f32 v[64:65], v[104:105], v[64:65], v[250:251]
	v_pk_fma_f32 v[66:67], v[106:107], v[66:67], v[252:253]
	v_cvt_pk_bf16_f32 v64, v64, v65
	v_cvt_pk_bf16_f32 v65, v66, v67
	v_lshl_add_u64 v[108:109], v[76:77], 0, s[4:5]
	global_store_dwordx2 v[108:109], v[64:65], off
	s_add_u32 s4, s4, 0x1000
	s_addc_u32 s5, s5, 0
	s_mov_b32 s12, 0x2000
	s_mov_b32 s13, 0
	s_waitcnt lgkmcnt(0)
	s_barrier
	s_add_i32 s22, s22, s34
	s_add_i32 s10, s10, s88
	s_cmpk_gt_i32 s22, 0x3ff
	s_cbranch_scc0 .Lnm_n1_loop
	s_branch .LBB0_182

.LBB0_989:
	v_mbcnt_lo_u32_b32 v112, -1, 0
	v_mbcnt_hi_u32_b32 v112, -1, v112
	v_and_b32_e32 v112, 15, v112
	v_lshlrev_b32_e32 v85, 2, v112
	s_lshl_b32 s17, s3, 6
	v_mov_b32_e32 v84, s17
	s_mov_b32 s12, 0x8000
	s_mov_b32 s13, 0
.Lnm_n2_loop:
	s_ashr_i32 s9, s8, 31
	s_lshl_b64 s[0:1], s[8:9], 13
	v_lshl_add_u64 v[110:111], v[76:77], 0, s[0:1]
	global_load_dwordx4 v[4:7], v[110:111], off
	s_add_u32 s0, s0, 0x2000
	s_addc_u32 s1, s1, 0
	v_lshl_add_u64 v[110:111], v[76:77], 0, s[0:1]
	global_load_dwordx4 v[8:11], v[110:111], off
	s_add_u32 s0, s0, 0x2000
	s_addc_u32 s1, s1, 0
	v_lshl_add_u64 v[110:111], v[76:77], 0, s[0:1]
	global_load_dwordx4 v[12:15], v[110:111], off
	s_add_u32 s0, s0, 0x2000
	s_addc_u32 s1, s1, 0
	v_lshl_add_u64 v[110:111], v[76:77], 0, s[0:1]
	global_load_dwordx4 v[16:19], v[110:111], off
	s_add_u32 s0, s0, 0x2000
	s_addc_u32 s1, s1, 0
	v_lshl_add_u64 v[110:111], v[76:77], 0, s[0:1]
	global_load_dwordx4 v[20:23], v[110:111], off
	s_add_u32 s0, s0, 0x2000
	s_addc_u32 s1, s1, 0
	v_lshl_add_u64 v[110:111], v[76:77], 0, s[0:1]
	global_load_dwordx4 v[24:27], v[110:111], off
	s_add_u32 s0, s0, 0x2000
	s_addc_u32 s1, s1, 0
	v_lshl_add_u64 v[110:111], v[76:77], 0, s[0:1]
	global_load_dwordx4 v[28:31], v[110:111], off
	s_add_u32 s0, s0, 0x2000
	s_addc_u32 s1, s1, 0
	v_lshl_add_u64 v[110:111], v[76:77], 0, s[0:1]
	global_load_dwordx4 v[32:35], v[110:111], off
	s_add_u32 s0, s0, 0x2000
	s_addc_u32 s1, s1, 0
	v_lshl_add_u64 v[110:111], v[76:77], 0, s[0:1]
	global_load_dwordx4 v[36:39], v[110:111], off
	s_add_u32 s0, s0, 0x2000
	s_addc_u32 s1, s1, 0
	v_lshl_add_u64 v[110:111], v[76:77], 0, s[0:1]
	global_load_dwordx4 v[40:43], v[110:111], off
	s_add_u32 s0, s0, 0x2000
	s_addc_u32 s1, s1, 0
	v_lshl_add_u64 v[110:111], v[76:77], 0, s[0:1]
	global_load_dwordx4 v[44:47], v[110:111], off
	s_add_u32 s0, s0, 0x2000
	s_addc_u32 s1, s1, 0
	v_lshl_add_u64 v[110:111], v[76:77], 0, s[0:1]
	global_load_dwordx4 v[48:51], v[110:111], off
	s_add_u32 s0, s0, 0x2000
	s_addc_u32 s1, s1, 0
	v_lshl_add_u64 v[110:111], v[76:77], 0, s[0:1]
	global_load_dwordx4 v[52:55], v[110:111], off
	s_add_u32 s0, s0, 0x2000
	s_addc_u32 s1, s1, 0
	v_lshl_add_u64 v[110:111], v[76:77], 0, s[0:1]
	global_load_dwordx4 v[56:59], v[110:111], off
	s_add_u32 s0, s0, 0x2000
	s_addc_u32 s1, s1, 0
	v_lshl_add_u64 v[110:111], v[76:77], 0, s[0:1]
	global_load_dwordx4 v[60:63], v[110:111], off
	s_add_u32 s0, s0, 0x2000
	s_addc_u32 s1, s1, 0
	v_lshl_add_u64 v[110:111], v[76:77], 0, s[0:1]
	global_load_dwordx4 v[64:67], v[110:111], off
	s_ashr_i32 s0, s20, 8
	v_mad_i64_i32 v[110:111], s[0:1], s0, v178, v[82:83]
	v_lshl_add_u64 v[112:113], v[110:111], 0, s[12:13]
	global_load_dwordx4 v[118:121], v[112:113], off
	s_mov_b32 s0, 0x6000
	s_mov_b32 s1, 0
	v_lshl_add_u64 v[112:113], v[110:111], 0, s[0:1]
	global_load_dwordx4 v[250:253], v[112:113], off
	s_waitcnt vmcnt(17)
	v_mul_f32_e32 v68, v5, v5
	v_mul_f32_e32 v102, v7, v7
	v_fmac_f32_e32 v68, v4, v4
	v_fmac_f32_e32 v102, v6, v6
	v_add_f32_e32 v68, v68, v102
	s_waitcnt vmcnt(16)
	v_mul_f32_e32 v69, v9, v9
	v_mul_f32_e32 v103, v11, v11
	v_fmac_f32_e32 v69, v8, v8
	v_fmac_f32_e32 v103, v10, v10
	v_add_f32_e32 v69, v69, v103
	s_waitcnt vmcnt(15)
	v_mul_f32_e32 v70, v13, v13
	v_mul_f32_e32 v104, v15, v15
	v_fmac_f32_e32 v70, v12, v12
	v_fmac_f32_e32 v104, v14, v14
	v_add_f32_e32 v70, v70, v104
	s_waitcnt vmcnt(14)
	v_mul_f32_e32 v71, v17, v17
	v_mul_f32_e32 v105, v19, v19
	v_fmac_f32_e32 v71, v16, v16
	v_fmac_f32_e32 v105, v18, v18
	v_add_f32_e32 v71, v71, v105
	s_waitcnt vmcnt(13)
	v_mul_f32_e32 v72, v21, v21
	v_mul_f32_e32 v106, v23, v23
	v_fmac_f32_e32 v72, v20, v20
	v_fmac_f32_e32 v106, v22, v22
	v_add_f32_e32 v72, v72, v106
	s_waitcnt vmcnt(12)
	v_mul_f32_e32 v73, v25, v25
	v_mul_f32_e32 v107, v27, v27
	v_fmac_f32_e32 v73, v24, v24
	v_fmac_f32_e32 v107, v26, v26
	v_add_f32_e32 v73, v73, v107
	s_waitcnt vmcnt(11)
	v_mul_f32_e32 v74, v29, v29
	v_mul_f32_e32 v108, v31, v31
	v_fmac_f32_e32 v74, v28, v28
	v_fmac_f32_e32 v108, v30, v30
	v_add_f32_e32 v74, v74, v108
	s_waitcnt vmcnt(10)
	v_mul_f32_e32 v75, v33, v33
	v_mul_f32_e32 v109, v35, v35
	v_fmac_f32_e32 v75, v32, v32
	v_fmac_f32_e32 v109, v34, v34
	v_add_f32_e32 v75, v75, v109
	s_waitcnt vmcnt(9)
	v_mul_f32_e32 v94, v37, v37
	v_mul_f32_e32 v110, v39, v39
	v_fmac_f32_e32 v94, v36, v36
	v_fmac_f32_e32 v110, v38, v38
	v_add_f32_e32 v94, v94, v110
	s_waitcnt vmcnt(8)
	v_mul_f32_e32 v95, v41, v41
	v_mul_f32_e32 v111, v43, v43
	v_fmac_f32_e32 v95, v40, v40
	v_fmac_f32_e32 v111, v42, v42
	v_add_f32_e32 v95, v95, v111
	s_waitcnt vmcnt(7)
	v_mul_f32_e32 v96, v45, v45
	v_mul_f32_e32 v112, v47, v47
	v_fmac_f32_e32 v96, v44, v44
	v_fmac_f32_e32 v112, v46, v46
	v_add_f32_e32 v96, v96, v112
	s_waitcnt vmcnt(6)
	v_mul_f32_e32 v97, v49, v49
	v_mul_f32_e32 v113, v51, v51
	v_fmac_f32_e32 v97, v48, v48
	v_fmac_f32_e32 v113, v50, v50
	v_add_f32_e32 v97, v97, v113
	s_waitcnt vmcnt(5)
	v_mul_f32_e32 v98, v53, v53
	v_mul_f32_e32 v114, v55, v55
	v_fmac_f32_e32 v98, v52, v52
	v_fmac_f32_e32 v114, v54, v54
	v_add_f32_e32 v98, v98, v114
	s_waitcnt vmcnt(4)
	v_mul_f32_e32 v99, v57, v57
	v_mul_f32_e32 v115, v59, v59
	v_fmac_f32_e32 v99, v56, v56
	v_fmac_f32_e32 v115, v58, v58
	v_add_f32_e32 v99, v99, v115
	s_waitcnt vmcnt(3)
	v_mul_f32_e32 v100, v61, v61
	v_mul_f32_e32 v116, v63, v63
	v_fmac_f32_e32 v100, v60, v60
	v_fmac_f32_e32 v116, v62, v62
	v_add_f32_e32 v100, v100, v116
	s_waitcnt vmcnt(2)
	v_mul_f32_e32 v101, v65, v65
	v_mul_f32_e32 v117, v67, v67
	v_fmac_f32_e32 v101, v64, v64
	v_fmac_f32_e32 v117, v66, v66
	v_add_f32_e32 v101, v101, v117
	ds_bpermute_b32 v102, v87, v68
	ds_bpermute_b32 v103, v87, v69
	ds_bpermute_b32 v104, v87, v70
	ds_bpermute_b32 v105, v87, v71
	ds_bpermute_b32 v106, v87, v72
	ds_bpermute_b32 v107, v87, v73
	ds_bpermute_b32 v108, v87, v74
	ds_bpermute_b32 v109, v87, v75
	ds_bpermute_b32 v110, v87, v94
	ds_bpermute_b32 v111, v87, v95
	ds_bpermute_b32 v112, v87, v96
	ds_bpermute_b32 v113, v87, v97
	ds_bpermute_b32 v114, v87, v98
	ds_bpermute_b32 v115, v87, v99
	ds_bpermute_b32 v116, v87, v100
	ds_bpermute_b32 v117, v87, v101
	s_waitcnt lgkmcnt(15)
	v_add_f32_e32 v68, v68, v102
	s_waitcnt lgkmcnt(14)
	v_add_f32_e32 v69, v69, v103
	s_waitcnt lgkmcnt(13)
	v_add_f32_e32 v70, v70, v104
	s_waitcnt lgkmcnt(12)
	v_add_f32_e32 v71, v71, v105
	s_waitcnt lgkmcnt(11)
	v_add_f32_e32 v72, v72, v106
	s_waitcnt lgkmcnt(10)
	v_add_f32_e32 v73, v73, v107
	s_waitcnt lgkmcnt(9)
	v_add_f32_e32 v74, v74, v108
	s_waitcnt lgkmcnt(8)
	v_add_f32_e32 v75, v75, v109
	s_waitcnt lgkmcnt(7)
	v_add_f32_e32 v94, v94, v110
	s_waitcnt lgkmcnt(6)
	v_add_f32_e32 v95, v95, v111
	s_waitcnt lgkmcnt(5)
	v_add_f32_e32 v96, v96, v112
	s_waitcnt lgkmcnt(4)
	v_add_f32_e32 v97, v97, v113
	s_waitcnt lgkmcnt(3)
	v_add_f32_e32 v98, v98, v114
	s_waitcnt lgkmcnt(2)
	v_add_f32_e32 v99, v99, v115
	s_waitcnt lgkmcnt(1)
	v_add_f32_e32 v100, v100, v116
	s_waitcnt lgkmcnt(0)
	v_add_f32_e32 v101, v101, v117
	ds_bpermute_b32 v102, v88, v68
	ds_bpermute_b32 v103, v88, v69
	ds_bpermute_b32 v104, v88, v70
	ds_bpermute_b32 v105, v88, v71
	ds_bpermute_b32 v106, v88, v72
	ds_bpermute_b32 v107, v88, v73
	ds_bpermute_b32 v108, v88, v74
	ds_bpermute_b32 v109, v88, v75
	ds_bpermute_b32 v110, v88, v94
	ds_bpermute_b32 v111, v88, v95
	ds_bpermute_b32 v112, v88, v96
	ds_bpermute_b32 v113, v88, v97
	ds_bpermute_b32 v114, v88, v98
	ds_bpermute_b32 v115, v88, v99
	ds_bpermute_b32 v116, v88, v100
	ds_bpermute_b32 v117, v88, v101
	s_waitcnt lgkmcnt(15)
	v_add_f32_e32 v68, v68, v102
	s_waitcnt lgkmcnt(14)
	v_add_f32_e32 v69, v69, v103
	s_waitcnt lgkmcnt(13)
	v_add_f32_e32 v70, v70, v104
	s_waitcnt lgkmcnt(12)
	v_add_f32_e32 v71, v71, v105
	s_waitcnt lgkmcnt(11)
	v_add_f32_e32 v72, v72, v106
	s_waitcnt lgkmcnt(10)
	v_add_f32_e32 v73, v73, v107
	s_waitcnt lgkmcnt(9)
	v_add_f32_e32 v74, v74, v108
	s_waitcnt lgkmcnt(8)
	v_add_f32_e32 v75, v75, v109
	s_waitcnt lgkmcnt(7)
	v_add_f32_e32 v94, v94, v110
	s_waitcnt lgkmcnt(6)
	v_add_f32_e32 v95, v95, v111
	s_waitcnt lgkmcnt(5)
	v_add_f32_e32 v96, v96, v112
	s_waitcnt lgkmcnt(4)
	v_add_f32_e32 v97, v97, v113
	s_waitcnt lgkmcnt(3)
	v_add_f32_e32 v98, v98, v114
	s_waitcnt lgkmcnt(2)
	v_add_f32_e32 v99, v99, v115
	s_waitcnt lgkmcnt(1)
	v_add_f32_e32 v100, v100, v116
	s_waitcnt lgkmcnt(0)
	v_add_f32_e32 v101, v101, v117
	ds_bpermute_b32 v102, v89, v68
	ds_bpermute_b32 v103, v89, v69
	ds_bpermute_b32 v104, v89, v70
	ds_bpermute_b32 v105, v89, v71
	ds_bpermute_b32 v106, v89, v72
	ds_bpermute_b32 v107, v89, v73
	ds_bpermute_b32 v108, v89, v74
	ds_bpermute_b32 v109, v89, v75
	ds_bpermute_b32 v110, v89, v94
	ds_bpermute_b32 v111, v89, v95
	ds_bpermute_b32 v112, v89, v96
	ds_bpermute_b32 v113, v89, v97
	ds_bpermute_b32 v114, v89, v98
	ds_bpermute_b32 v115, v89, v99
	ds_bpermute_b32 v116, v89, v100
	ds_bpermute_b32 v117, v89, v101
	s_waitcnt lgkmcnt(15)
	v_add_f32_e32 v68, v68, v102
	s_waitcnt lgkmcnt(14)
	v_add_f32_e32 v69, v69, v103
	s_waitcnt lgkmcnt(13)
	v_add_f32_e32 v70, v70, v104
	s_waitcnt lgkmcnt(12)
	v_add_f32_e32 v71, v71, v105
	s_waitcnt lgkmcnt(11)
	v_add_f32_e32 v72, v72, v106
	s_waitcnt lgkmcnt(10)
	v_add_f32_e32 v73, v73, v107
	s_waitcnt lgkmcnt(9)
	v_add_f32_e32 v74, v74, v108
	s_waitcnt lgkmcnt(8)
	v_add_f32_e32 v75, v75, v109
	s_waitcnt lgkmcnt(7)
	v_add_f32_e32 v94, v94, v110
	s_waitcnt lgkmcnt(6)
	v_add_f32_e32 v95, v95, v111
	s_waitcnt lgkmcnt(5)
	v_add_f32_e32 v96, v96, v112
	s_waitcnt lgkmcnt(4)
	v_add_f32_e32 v97, v97, v113
	s_waitcnt lgkmcnt(3)
	v_add_f32_e32 v98, v98, v114
	s_waitcnt lgkmcnt(2)
	v_add_f32_e32 v99, v99, v115
	s_waitcnt lgkmcnt(1)
	v_add_f32_e32 v100, v100, v116
	s_waitcnt lgkmcnt(0)
	v_add_f32_e32 v101, v101, v117
	ds_bpermute_b32 v102, v90, v68
	ds_bpermute_b32 v103, v90, v69
	ds_bpermute_b32 v104, v90, v70
	ds_bpermute_b32 v105, v90, v71
	ds_bpermute_b32 v106, v90, v72
	ds_bpermute_b32 v107, v90, v73
	ds_bpermute_b32 v108, v90, v74
	ds_bpermute_b32 v109, v90, v75
	ds_bpermute_b32 v110, v90, v94
	ds_bpermute_b32 v111, v90, v95
	ds_bpermute_b32 v112, v90, v96
	ds_bpermute_b32 v113, v90, v97
	ds_bpermute_b32 v114, v90, v98
	ds_bpermute_b32 v115, v90, v99
	ds_bpermute_b32 v116, v90, v100
	ds_bpermute_b32 v117, v90, v101
	s_waitcnt lgkmcnt(15)
	v_add_f32_e32 v68, v68, v102
	s_waitcnt lgkmcnt(14)
	v_add_f32_e32 v69, v69, v103
	s_waitcnt lgkmcnt(13)
	v_add_f32_e32 v70, v70, v104
	s_waitcnt lgkmcnt(12)
	v_add_f32_e32 v71, v71, v105
	s_waitcnt lgkmcnt(11)
	v_add_f32_e32 v72, v72, v106
	s_waitcnt lgkmcnt(10)
	v_add_f32_e32 v73, v73, v107
	s_waitcnt lgkmcnt(9)
	v_add_f32_e32 v74, v74, v108
	s_waitcnt lgkmcnt(8)
	v_add_f32_e32 v75, v75, v109
	s_waitcnt lgkmcnt(7)
	v_add_f32_e32 v94, v94, v110
	s_waitcnt lgkmcnt(6)
	v_add_f32_e32 v95, v95, v111
	s_waitcnt lgkmcnt(5)
	v_add_f32_e32 v96, v96, v112
	s_waitcnt lgkmcnt(4)
	v_add_f32_e32 v97, v97, v113
	s_waitcnt lgkmcnt(3)
	v_add_f32_e32 v98, v98, v114
	s_waitcnt lgkmcnt(2)
	v_add_f32_e32 v99, v99, v115
	s_waitcnt lgkmcnt(1)
	v_add_f32_e32 v100, v100, v116
	s_waitcnt lgkmcnt(0)
	v_add_f32_e32 v101, v101, v117
	ds_bpermute_b32 v102, v91, v68
	ds_bpermute_b32 v103, v91, v69
	ds_bpermute_b32 v104, v91, v70
	ds_bpermute_b32 v105, v91, v71
	ds_bpermute_b32 v106, v91, v72
	ds_bpermute_b32 v107, v91, v73
	ds_bpermute_b32 v108, v91, v74
	ds_bpermute_b32 v109, v91, v75
	ds_bpermute_b32 v110, v91, v94
	ds_bpermute_b32 v111, v91, v95
	ds_bpermute_b32 v112, v91, v96
	ds_bpermute_b32 v113, v91, v97
	ds_bpermute_b32 v114, v91, v98
	ds_bpermute_b32 v115, v91, v99
	ds_bpermute_b32 v116, v91, v100
	ds_bpermute_b32 v117, v91, v101
	s_waitcnt lgkmcnt(15)
	v_add_f32_e32 v68, v68, v102
	s_waitcnt lgkmcnt(14)
	v_add_f32_e32 v69, v69, v103
	s_waitcnt lgkmcnt(13)
	v_add_f32_e32 v70, v70, v104
	s_waitcnt lgkmcnt(12)
	v_add_f32_e32 v71, v71, v105
	s_waitcnt lgkmcnt(11)
	v_add_f32_e32 v72, v72, v106
	s_waitcnt lgkmcnt(10)
	v_add_f32_e32 v73, v73, v107
	s_waitcnt lgkmcnt(9)
	v_add_f32_e32 v74, v74, v108
	s_waitcnt lgkmcnt(8)
	v_add_f32_e32 v75, v75, v109
	s_waitcnt lgkmcnt(7)
	v_add_f32_e32 v94, v94, v110
	s_waitcnt lgkmcnt(6)
	v_add_f32_e32 v95, v95, v111
	s_waitcnt lgkmcnt(5)
	v_add_f32_e32 v96, v96, v112
	s_waitcnt lgkmcnt(4)
	v_add_f32_e32 v97, v97, v113
	s_waitcnt lgkmcnt(3)
	v_add_f32_e32 v98, v98, v114
	s_waitcnt lgkmcnt(2)
	v_add_f32_e32 v99, v99, v115
	s_waitcnt lgkmcnt(1)
	v_add_f32_e32 v100, v100, v116
	s_waitcnt lgkmcnt(0)
	v_add_f32_e32 v101, v101, v117
	ds_bpermute_b32 v102, v92, v68
	ds_bpermute_b32 v103, v92, v69
	ds_bpermute_b32 v104, v92, v70
	ds_bpermute_b32 v105, v92, v71
	ds_bpermute_b32 v106, v92, v72
	ds_bpermute_b32 v107, v92, v73
	ds_bpermute_b32 v108, v92, v74
	ds_bpermute_b32 v109, v92, v75
	ds_bpermute_b32 v110, v92, v94
	ds_bpermute_b32 v111, v92, v95
	ds_bpermute_b32 v112, v92, v96
	ds_bpermute_b32 v113, v92, v97
	ds_bpermute_b32 v114, v92, v98
	ds_bpermute_b32 v115, v92, v99
	ds_bpermute_b32 v116, v92, v100
	ds_bpermute_b32 v117, v92, v101
	s_waitcnt lgkmcnt(15)
	v_add_f32_e32 v68, v68, v102
	s_waitcnt lgkmcnt(14)
	v_add_f32_e32 v69, v69, v103
	s_waitcnt lgkmcnt(13)
	v_add_f32_e32 v70, v70, v104
	s_waitcnt lgkmcnt(12)
	v_add_f32_e32 v71, v71, v105
	s_waitcnt lgkmcnt(11)
	v_add_f32_e32 v72, v72, v106
	s_waitcnt lgkmcnt(10)
	v_add_f32_e32 v73, v73, v107
	s_waitcnt lgkmcnt(9)
	v_add_f32_e32 v74, v74, v108
	s_waitcnt lgkmcnt(8)
	v_add_f32_e32 v75, v75, v109
	s_waitcnt lgkmcnt(7)
	v_add_f32_e32 v94, v94, v110
	s_waitcnt lgkmcnt(6)
	v_add_f32_e32 v95, v95, v111
	s_waitcnt lgkmcnt(5)
	v_add_f32_e32 v96, v96, v112
	s_waitcnt lgkmcnt(4)
	v_add_f32_e32 v97, v97, v113
	s_waitcnt lgkmcnt(3)
	v_add_f32_e32 v98, v98, v114
	s_waitcnt lgkmcnt(2)
	v_add_f32_e32 v99, v99, v115
	s_waitcnt lgkmcnt(1)
	v_add_f32_e32 v100, v100, v116
	s_waitcnt lgkmcnt(0)
	v_add_f32_e32 v101, v101, v117
	s_mov_b64 exec, 1
	ds_write_b128 v84, v[68:71]
	ds_write_b128 v84, v[72:75] offset:16
	ds_write_b128 v84, v[94:97] offset:32
	ds_write_b128 v84, v[98:101] offset:48
	s_mov_b64 exec, -1
	s_waitcnt lgkmcnt(0)
	s_barrier
	ds_read_b32 v102, v85
	ds_read_b32 v103, v85 offset:64
	ds_read_b32 v104, v85 offset:128
	ds_read_b32 v105, v85 offset:192
	ds_read_b32 v106, v85 offset:256
	ds_read_b32 v107, v85 offset:320
	ds_read_b32 v108, v85 offset:384
	ds_read_b32 v109, v85 offset:448
	s_waitcnt lgkmcnt(0)
	v_add_f32_e32 v102, v102, v103
	v_add_f32_e32 v104, v104, v105
	v_add_f32_e32 v106, v106, v107
	v_add_f32_e32 v108, v108, v109
	v_add_f32_e32 v102, v102, v104
	v_add_f32_e32 v106, v106, v108
	v_add_f32_e32 v102, v102, v106
	v_fmamk_f32 v102, v102, 0x3a000000, v173
	v_cmp_gt_f32_e32 vcc, s33, v102
	v_mul_f32_e32 v116, 0x4f800000, v102
	s_nop 1
	v_cndmask_b32_e32 v102, v102, v116, vcc
	v_sqrt_f32_e32 v116, v102
	s_nop 1
	v_add_u32_e32 v111, -1, v116
	v_fma_f32 v112, -v111, v116, v102
	v_cmp_ge_f32_e64 s[14:15], 0, v112
	v_add_u32_e32 v112, 1, v116
	s_nop 1
	v_cndmask_b32_e64 v111, v116, v111, s[14:15]
	v_fma_f32 v116, -v112, v116, v102
	v_cmp_lt_f32_e64 s[14:15], 0, v116
	s_nop 1
	v_cndmask_b32_e64 v116, v111, v112, s[14:15]
	v_mul_f32_e32 v111, 0x37800000, v116
	v_cndmask_b32_e32 v116, v116, v111, vcc
	v_cmp_class_f32_e32 vcc, v102, v174
	s_nop 1
	v_cndmask_b32_e32 v102, v116, v102, vcc
	v_div_scale_f32 v116, s[16:17], v102, v102, 1.0
	v_rcp_f32_e32 v111, v116
	s_nop 0
	v_fma_f32 v112, -v116, v111, 1.0
	v_fmac_f32_e32 v111, v112, v111
	v_div_scale_f32 v112, vcc, 1.0, v102, 1.0
	v_mul_f32_e32 v113, v112, v111
	v_fma_f32 v114, -v116, v113, v112
	v_fmac_f32_e32 v113, v114, v111
	v_fma_f32 v116, -v116, v113, v112
	v_div_fmas_f32 v116, v116, v111, v113
	v_div_fixup_f32 v116, v116, v102, 1.0
	s_waitcnt vmcnt(0)
	v_pk_add_f32 v[118:119], v[118:119], 1.0 op_sel_hi:[1,0]
	v_pk_add_f32 v[120:121], v[120:121], 1.0 op_sel_hi:[1,0]
	v_pk_mul_f32 v[104:105], v[0:1], v[118:119]
	v_pk_mul_f32 v[106:107], v[2:3], v[120:121]
	s_ashr_i32 s9, s8, 31
	s_lshl_b64 s[6:7], s[8:9], 12
	v_readlane_b32 s0, v116, 0
	v_readlane_b32 s1, v116, 1
	v_readlane_b32 s9, v116, 2
	v_readlane_b32 s10, v116, 3
	v_readlane_b32 s11, v116, 4
	v_readlane_b32 s12, v116, 5
	v_readlane_b32 s13, v116, 6
	v_readlane_b32 s14, v116, 7
	s_nop 1
	v_mul_f32_e32 v4, s0, v4
	v_mul_f32_e32 v5, s0, v5
	v_mul_f32_e32 v6, s0, v6
	v_mul_f32_e32 v7, s0, v7
	v_pk_fma_f32 v[4:5], v[104:105], v[4:5], v[250:251]
	v_pk_fma_f32 v[6:7], v[106:107], v[6:7], v[252:253]
	v_cvt_pk_bf16_f32 v4, v4, v5
	v_cvt_pk_bf16_f32 v5, v6, v7
	v_lshl_add_u64 v[108:109], v[78:79], 0, s[6:7]
	global_store_dwordx2 v[108:109], v[4:5], off
	s_add_u32 s6, s6, 0x1000
	s_addc_u32 s7, s7, 0
	v_mul_f32_e32 v8, s1, v8
	v_mul_f32_e32 v9, s1, v9
	v_mul_f32_e32 v10, s1, v10
	v_mul_f32_e32 v11, s1, v11
	v_pk_fma_f32 v[8:9], v[104:105], v[8:9], v[250:251]
	v_pk_fma_f32 v[10:11], v[106:107], v[10:11], v[252:253]
	v_cvt_pk_bf16_f32 v8, v8, v9
	v_cvt_pk_bf16_f32 v9, v10, v11
	v_lshl_add_u64 v[108:109], v[78:79], 0, s[6:7]
	global_store_dwordx2 v[108:109], v[8:9], off
	s_add_u32 s6, s6, 0x1000
	s_addc_u32 s7, s7, 0
	v_mul_f32_e32 v12, s9, v12
	v_mul_f32_e32 v13, s9, v13
	v_mul_f32_e32 v14, s9, v14
	v_mul_f32_e32 v15, s9, v15
	v_pk_fma_f32 v[12:13], v[104:105], v[12:13], v[250:251]
	v_pk_fma_f32 v[14:15], v[106:107], v[14:15], v[252:253]
	v_cvt_pk_bf16_f32 v12, v12, v13
	v_cvt_pk_bf16_f32 v13, v14, v15
	v_lshl_add_u64 v[108:109], v[78:79], 0, s[6:7]
	global_store_dwordx2 v[108:109], v[12:13], off
	s_add_u32 s6, s6, 0x1000
	s_addc_u32 s7, s7, 0
	v_mul_f32_e32 v16, s10, v16
	v_mul_f32_e32 v17, s10, v17
	v_mul_f32_e32 v18, s10, v18
	v_mul_f32_e32 v19, s10, v19
	v_pk_fma_f32 v[16:17], v[104:105], v[16:17], v[250:251]
	v_pk_fma_f32 v[18:19], v[106:107], v[18:19], v[252:253]
	v_cvt_pk_bf16_f32 v16, v16, v17
	v_cvt_pk_bf16_f32 v17, v18, v19
	v_lshl_add_u64 v[108:109], v[78:79], 0, s[6:7]
	global_store_dwordx2 v[108:109], v[16:17], off
	s_add_u32 s6, s6, 0x1000
	s_addc_u32 s7, s7, 0
	v_mul_f32_e32 v20, s11, v20
	v_mul_f32_e32 v21, s11, v21
	v_mul_f32_e32 v22, s11, v22
	v_mul_f32_e32 v23, s11, v23
	v_pk_fma_f32 v[20:21], v[104:105], v[20:21], v[250:251]
	v_pk_fma_f32 v[22:23], v[106:107], v[22:23], v[252:253]
	v_cvt_pk_bf16_f32 v20, v20, v21
	v_cvt_pk_bf16_f32 v21, v22, v23
	v_lshl_add_u64 v[108:109], v[78:79], 0, s[6:7]
	global_store_dwordx2 v[108:109], v[20:21], off
	s_add_u32 s6, s6, 0x1000
	s_addc_u32 s7, s7, 0
	v_mul_f32_e32 v24, s12, v24
	v_mul_f32_e32 v25, s12, v25
	v_mul_f32_e32 v26, s12, v26
	v_mul_f32_e32 v27, s12, v27
	v_pk_fma_f32 v[24:25], v[104:105], v[24:25], v[250:251]
	v_pk_fma_f32 v[26:27], v[106:107], v[26:27], v[252:253]
	v_cvt_pk_bf16_f32 v24, v24, v25
	v_cvt_pk_bf16_f32 v25, v26, v27
	v_lshl_add_u64 v[108:109], v[78:79], 0, s[6:7]
	global_store_dwordx2 v[108:109], v[24:25], off
	s_add_u32 s6, s6, 0x1000
	s_addc_u32 s7, s7, 0
	v_mul_f32_e32 v28, s13, v28
	v_mul_f32_e32 v29, s13, v29
	v_mul_f32_e32 v30, s13, v30
	v_mul_f32_e32 v31, s13, v31
	v_pk_fma_f32 v[28:29], v[104:105], v[28:29], v[250:251]
	v_pk_fma_f32 v[30:31], v[106:107], v[30:31], v[252:253]
	v_cvt_pk_bf16_f32 v28, v28, v29
	v_cvt_pk_bf16_f32 v29, v30, v31
	v_lshl_add_u64 v[108:109], v[78:79], 0, s[6:7]
	global_store_dwordx2 v[108:109], v[28:29], off
	s_add_u32 s6, s6, 0x1000
	s_addc_u32 s7, s7, 0
	v_mul_f32_e32 v32, s14, v32
	v_mul_f32_e32 v33, s14, v33
	v_mul_f32_e32 v34, s14, v34
	v_mul_f32_e32 v35, s14, v35
	v_pk_fma_f32 v[32:33], v[104:105], v[32:33], v[250:251]
	v_pk_fma_f32 v[34:35], v[106:107], v[34:35], v[252:253]
	v_cvt_pk_bf16_f32 v32, v32, v33
	v_cvt_pk_bf16_f32 v33, v34, v35
	v_lshl_add_u64 v[108:109], v[78:79], 0, s[6:7]
	global_store_dwordx2 v[108:109], v[32:33], off
	s_add_u32 s6, s6, 0x1000
	s_addc_u32 s7, s7, 0
	v_readlane_b32 s0, v116, 8
	v_readlane_b32 s1, v116, 9
	v_readlane_b32 s9, v116, 10
	v_readlane_b32 s10, v116, 11
	v_readlane_b32 s11, v116, 12
	v_readlane_b32 s12, v116, 13
	v_readlane_b32 s13, v116, 14
	v_readlane_b32 s14, v116, 15
	s_nop 1
	v_mul_f32_e32 v36, s0, v36
	v_mul_f32_e32 v37, s0, v37
	v_mul_f32_e32 v38, s0, v38
	v_mul_f32_e32 v39, s0, v39
	v_pk_fma_f32 v[36:37], v[104:105], v[36:37], v[250:251]
	v_pk_fma_f32 v[38:39], v[106:107], v[38:39], v[252:253]
	v_cvt_pk_bf16_f32 v36, v36, v37
	v_cvt_pk_bf16_f32 v37, v38, v39
	v_lshl_add_u64 v[108:109], v[78:79], 0, s[6:7]
	global_store_dwordx2 v[108:109], v[36:37], off
	s_add_u32 s6, s6, 0x1000
	s_addc_u32 s7, s7, 0
	v_mul_f32_e32 v40, s1, v40
	v_mul_f32_e32 v41, s1, v41
	v_mul_f32_e32 v42, s1, v42
	v_mul_f32_e32 v43, s1, v43
	v_pk_fma_f32 v[40:41], v[104:105], v[40:41], v[250:251]
	v_pk_fma_f32 v[42:43], v[106:107], v[42:43], v[252:253]
	v_cvt_pk_bf16_f32 v40, v40, v41
	v_cvt_pk_bf16_f32 v41, v42, v43
	v_lshl_add_u64 v[108:109], v[78:79], 0, s[6:7]
	global_store_dwordx2 v[108:109], v[40:41], off
	s_add_u32 s6, s6, 0x1000
	s_addc_u32 s7, s7, 0
	v_mul_f32_e32 v44, s9, v44
	v_mul_f32_e32 v45, s9, v45
	v_mul_f32_e32 v46, s9, v46
	v_mul_f32_e32 v47, s9, v47
	v_pk_fma_f32 v[44:45], v[104:105], v[44:45], v[250:251]
	v_pk_fma_f32 v[46:47], v[106:107], v[46:47], v[252:253]
	v_cvt_pk_bf16_f32 v44, v44, v45
	v_cvt_pk_bf16_f32 v45, v46, v47
	v_lshl_add_u64 v[108:109], v[78:79], 0, s[6:7]
	global_store_dwordx2 v[108:109], v[44:45], off
	s_add_u32 s6, s6, 0x1000
	s_addc_u32 s7, s7, 0
	v_mul_f32_e32 v48, s10, v48
	v_mul_f32_e32 v49, s10, v49
	v_mul_f32_e32 v50, s10, v50
	v_mul_f32_e32 v51, s10, v51
	v_pk_fma_f32 v[48:49], v[104:105], v[48:49], v[250:251]
	v_pk_fma_f32 v[50:51], v[106:107], v[50:51], v[252:253]
	v_cvt_pk_bf16_f32 v48, v48, v49
	v_cvt_pk_bf16_f32 v49, v50, v51
	v_lshl_add_u64 v[108:109], v[78:79], 0, s[6:7]
	global_store_dwordx2 v[108:109], v[48:49], off
	s_add_u32 s6, s6, 0x1000
	s_addc_u32 s7, s7, 0
	v_mul_f32_e32 v52, s11, v52
	v_mul_f32_e32 v53, s11, v53
	v_mul_f32_e32 v54, s11, v54
	v_mul_f32_e32 v55, s11, v55
	v_pk_fma_f32 v[52:53], v[104:105], v[52:53], v[250:251]
	v_pk_fma_f32 v[54:55], v[106:107], v[54:55], v[252:253]
	v_cvt_pk_bf16_f32 v52, v52, v53
	v_cvt_pk_bf16_f32 v53, v54, v55
	v_lshl_add_u64 v[108:109], v[78:79], 0, s[6:7]
	global_store_dwordx2 v[108:109], v[52:53], off
	s_add_u32 s6, s6, 0x1000
	s_addc_u32 s7, s7, 0
	v_mul_f32_e32 v56, s12, v56
	v_mul_f32_e32 v57, s12, v57
	v_mul_f32_e32 v58, s12, v58
	v_mul_f32_e32 v59, s12, v59
	v_pk_fma_f32 v[56:57], v[104:105], v[56:57], v[250:251]
	v_pk_fma_f32 v[58:59], v[106:107], v[58:59], v[252:253]
	v_cvt_pk_bf16_f32 v56, v56, v57
	v_cvt_pk_bf16_f32 v57, v58, v59
	v_lshl_add_u64 v[108:109], v[78:79], 0, s[6:7]
	global_store_dwordx2 v[108:109], v[56:57], off
	s_add_u32 s6, s6, 0x1000
	s_addc_u32 s7, s7, 0
	v_mul_f32_e32 v60, s13, v60
	v_mul_f32_e32 v61, s13, v61
	v_mul_f32_e32 v62, s13, v62
	v_mul_f32_e32 v63, s13, v63
	v_pk_fma_f32 v[60:61], v[104:105], v[60:61], v[250:251]
	v_pk_fma_f32 v[62:63], v[106:107], v[62:63], v[252:253]
	v_cvt_pk_bf16_f32 v60, v60, v61
	v_cvt_pk_bf16_f32 v61, v62, v63
	v_lshl_add_u64 v[108:109], v[78:79], 0, s[6:7]
	global_store_dwordx2 v[108:109], v[60:61], off
	s_add_u32 s6, s6, 0x1000
	s_addc_u32 s7, s7, 0
	v_mul_f32_e32 v64, s14, v64
	v_mul_f32_e32 v65, s14, v65
	v_mul_f32_e32 v66, s14, v66
	v_mul_f32_e32 v67, s14, v67
	v_pk_fma_f32 v[64:65], v[104:105], v[64:65], v[250:251]
	v_pk_fma_f32 v[66:67], v[106:107], v[66:67], v[252:253]
	v_cvt_pk_bf16_f32 v64, v64, v65
	v_cvt_pk_bf16_f32 v65, v66, v67
	v_lshl_add_u64 v[108:109], v[78:79], 0, s[6:7]
	global_store_dwordx2 v[108:109], v[64:65], off
	s_add_u32 s6, s6, 0x1000
	s_addc_u32 s7, s7, 0
	s_mov_b32 s12, 0x8000
	s_mov_b32 s13, 0
	s_waitcnt lgkmcnt(0)
	s_barrier
	s_add_i32 s20, s20, s34
	s_add_i32 s8, s8, s88
	s_cmpk_gt_i32 s20, 0x3ff
	s_cbranch_scc0 .Lnm_n2_loop
	s_branch .LBB0_1048
